# G5/G7 residual epilogues: gate-vector and 16 residual loads issued up front, fma+store streamed behind counted waits (was one load at a time)
# speedup vs baseline: 1.0257x; 1.0060x over previous
.LBB0_99:
	s_and_b32 s2, s47, 64
	s_add_i32 s3, s48, 0xfffff000
	s_lshr_b32 s3, s3, 11
	s_add_i32 s3, s3, 1
	s_cmp_gt_i32 s46, 31
	v_readlane_b32 s18, v254, 61
	s_cselect_b32 s3, s3, 0
	s_mul_i32 s1, s18, 5
	s_add_i32 s3, s3, s1
	v_readlane_b32 s52, v254, 48
	s_mul_hi_i32 s20, s3, 0x6000
	s_mulk_i32 s3, 0x6000
	v_readlane_b32 s56, v254, 52
	v_readlane_b32 s57, v254, 53
	s_add_u32 s3, s56, s3
	s_addc_u32 s20, s57, s20
	s_add_u32 s40, s3, 0x9000
	v_lshrrev_b32_e32 v1, 2, v0
	s_addc_u32 s41, s20, 0
	v_and_or_b32 v1, v1, 12, s2
	s_ashr_i32 s2, s47, 1
	s_andn2_b32 s2, s2, 63
	s_add_i32 s2, s2, s48
	v_lshl_or_b32 v70, s45, 7, v1
	v_and_or_b32 v80, v0, 15, s2
	v_mov_b32_e32 v71, v2
	v_readlane_b32 s54, v254, 50
	v_readlane_b32 s55, v254, 51
	v_ashrrev_i32_e32 v81, 31, v80
	v_lshlrev_b64 v[68:69], 2, v[70:71]
	v_lshlrev_b64 v[0:1], 12, v[80:81]
	v_lshl_add_u64 v[82:83], s[54:55], 0, v[68:69]
	v_lshl_add_u64 v[72:73], s[40:41], 0, v[68:69]
	v_lshl_add_u64 v[68:69], v[82:83], 0, v[0:1]
	v_or_b32_e32 v0, 16, v80
	v_ashrrev_i32_e32 v1, 31, v0
	v_lshlrev_b64 v[0:1], 12, v[0:1]
	v_lshl_add_u64 v[0:1], v[82:83], 0, v[0:1]
	v_or_b32_e32 v84, 32, v80
	v_ashrrev_i32_e32 v85, 31, v84
	v_lshlrev_b64 v[84:85], 12, v[84:85]
	v_lshl_add_u64 v[84:85], v[82:83], 0, v[84:85]
	v_or_b32_e32 v86, 48, v80
	v_ashrrev_i32_e32 v87, 31, v86
	v_lshlrev_b64 v[86:87], 12, v[86:87]
	v_lshl_add_u64 v[86:87], v[82:83], 0, v[86:87]
	v_or_b32_e32 v88, 16, v70
	v_mov_b32_e32 v89, v2
	v_lshl_add_u64 v[88:89], v[88:89], 2, s[40:41]
	v_or_b32_e32 v90, 32, v70
	v_mov_b32_e32 v91, v2
	v_lshl_add_u64 v[90:91], v[90:91], 2, s[40:41]
	v_or_b32_e32 v92, 48, v70
	v_mov_b32_e32 v93, v2
	v_lshl_add_u64 v[92:93], v[92:93], 2, s[40:41]
	s_and_b64 vcc, exec, s[36:37]
	s_mov_b32 s45, s43
	s_mov_b32 s46, s42
	s_movk_i32 s35, 0x2fff
	v_readlane_b32 s19, v254, 62
	v_readlane_b32 s53, v254, 49
	v_readlane_b32 s58, v254, 54
	v_readlane_b32 s59, v254, 55
	s_mov_b64 s[40:41], 0
	global_load_dwordx4 v[72:75], v[72:73], off
	global_load_dwordx4 v[100:103], v[88:89], off
	global_load_dwordx4 v[104:107], v[90:91], off
	global_load_dwordx4 v[108:111], v[92:93], off
	global_load_dwordx4 v[112:115], v[68:69], off
	global_load_dwordx4 v[116:119], v[0:1], off
	global_load_dwordx4 v[120:123], v[84:85], off
	global_load_dwordx4 v[124:127], v[86:87], off
	global_load_dwordx4 v[128:131], v[68:69], off offset:64
	global_load_dwordx4 v[132:135], v[0:1], off offset:64
	global_load_dwordx4 v[136:139], v[84:85], off offset:64
	global_load_dwordx4 v[140:143], v[86:87], off offset:64
	global_load_dwordx4 v[144:147], v[68:69], off offset:128
	global_load_dwordx4 v[148:151], v[0:1], off offset:128
	global_load_dwordx4 v[152:155], v[84:85], off offset:128
	global_load_dwordx4 v[156:159], v[86:87], off offset:128
	global_load_dwordx4 v[160:163], v[68:69], off offset:192
	global_load_dwordx4 v[164:167], v[0:1], off offset:192
	global_load_dwordx4 v[76:79], v[84:85], off offset:192
	global_load_dwordx4 v[94:97], v[86:87], off offset:192
	s_waitcnt vmcnt(15)
	v_pk_fma_f32 v[66:67], v[66:67], v[74:75], v[114:115]
	v_pk_fma_f32 v[64:65], v[64:65], v[72:73], v[112:113]
	global_store_dwordx4 v[68:69], v[64:67], off
	s_waitcnt vmcnt(15)
	v_pk_fma_f32 v[62:63], v[62:63], v[74:75], v[118:119]
	v_pk_fma_f32 v[60:61], v[60:61], v[72:73], v[116:117]
	global_store_dwordx4 v[0:1], v[60:63], off
	s_waitcnt vmcnt(15)
	v_pk_fma_f32 v[58:59], v[58:59], v[74:75], v[122:123]
	v_pk_fma_f32 v[56:57], v[56:57], v[72:73], v[120:121]
	global_store_dwordx4 v[84:85], v[56:59], off
	s_waitcnt vmcnt(15)
	v_pk_fma_f32 v[54:55], v[54:55], v[74:75], v[126:127]
	v_pk_fma_f32 v[52:53], v[52:53], v[72:73], v[124:125]
	global_store_dwordx4 v[86:87], v[52:55], off
	s_waitcnt vmcnt(15)
	v_pk_fma_f32 v[50:51], v[50:51], v[102:103], v[130:131]
	v_pk_fma_f32 v[48:49], v[48:49], v[100:101], v[128:129]
	global_store_dwordx4 v[68:69], v[48:51], off offset:64
	s_waitcnt vmcnt(15)
	v_pk_fma_f32 v[46:47], v[46:47], v[102:103], v[134:135]
	v_pk_fma_f32 v[44:45], v[44:45], v[100:101], v[132:133]
	global_store_dwordx4 v[0:1], v[44:47], off offset:64
	s_waitcnt vmcnt(15)
	v_pk_fma_f32 v[42:43], v[42:43], v[102:103], v[138:139]
	v_pk_fma_f32 v[40:41], v[40:41], v[100:101], v[136:137]
	global_store_dwordx4 v[84:85], v[40:43], off offset:64
	s_waitcnt vmcnt(15)
	v_pk_fma_f32 v[38:39], v[38:39], v[102:103], v[142:143]
	v_pk_fma_f32 v[36:37], v[36:37], v[100:101], v[140:141]
	global_store_dwordx4 v[86:87], v[36:39], off offset:64
	s_waitcnt vmcnt(15)
	v_pk_fma_f32 v[34:35], v[34:35], v[106:107], v[146:147]
	v_pk_fma_f32 v[32:33], v[32:33], v[104:105], v[144:145]
	global_store_dwordx4 v[68:69], v[32:35], off offset:128
	s_waitcnt vmcnt(15)
	v_pk_fma_f32 v[30:31], v[30:31], v[106:107], v[150:151]
	v_pk_fma_f32 v[28:29], v[28:29], v[104:105], v[148:149]
	global_store_dwordx4 v[0:1], v[28:31], off offset:128
	s_waitcnt vmcnt(15)
	v_pk_fma_f32 v[26:27], v[26:27], v[106:107], v[154:155]
	v_pk_fma_f32 v[24:25], v[24:25], v[104:105], v[152:153]
	global_store_dwordx4 v[84:85], v[24:27], off offset:128
	s_waitcnt vmcnt(15)
	v_pk_fma_f32 v[22:23], v[22:23], v[106:107], v[158:159]
	v_pk_fma_f32 v[20:21], v[20:21], v[104:105], v[156:157]
	global_store_dwordx4 v[86:87], v[20:23], off offset:128
	s_waitcnt vmcnt(15)
	v_pk_fma_f32 v[18:19], v[18:19], v[110:111], v[162:163]
	v_pk_fma_f32 v[16:17], v[16:17], v[108:109], v[160:161]
	global_store_dwordx4 v[68:69], v[16:19], off offset:192
	s_waitcnt vmcnt(15)
	v_pk_fma_f32 v[14:15], v[14:15], v[110:111], v[166:167]
	v_pk_fma_f32 v[12:13], v[12:13], v[108:109], v[164:165]
	global_store_dwordx4 v[0:1], v[12:15], off offset:192
	s_waitcnt vmcnt(15)
	v_pk_fma_f32 v[10:11], v[10:11], v[110:111], v[78:79]
	v_pk_fma_f32 v[8:9], v[8:9], v[108:109], v[76:77]
	global_store_dwordx4 v[84:85], v[8:11], off offset:192
	s_waitcnt vmcnt(15)
	v_pk_fma_f32 v[6:7], v[6:7], v[110:111], v[96:97]
	v_pk_fma_f32 v[4:5], v[4:5], v[108:109], v[94:95]
	global_store_dwordx4 v[86:87], v[4:7], off offset:192
	s_cbranch_vccnz .LBB0_108

.LBB0_143:
	s_and_b32 s2, s49, 64
	s_add_i32 s3, s38, 0xfffff000
	s_lshr_b32 s3, s3, 11
	s_add_i32 s3, s3, 1
	s_cmp_gt_i32 s48, 31
	v_readlane_b32 s18, v254, 61
	s_cselect_b32 s3, s3, 0
	s_mul_i32 s1, s18, 5
	s_add_i32 s3, s3, s1
	v_readlane_b32 s52, v254, 48
	s_mul_hi_i32 s20, s3, 0x6000
	s_mulk_i32 s3, 0x6000
	v_readlane_b32 s56, v254, 52
	v_readlane_b32 s57, v254, 53
	s_add_u32 s3, s56, s3
	s_addc_u32 s20, s57, s20
	s_add_u32 s42, s3, 0x6000
	v_lshrrev_b32_e32 v1, 2, v0
	s_addc_u32 s43, s20, 0
	v_and_or_b32 v1, v1, 12, s2
	s_ashr_i32 s2, s49, 1
	s_andn2_b32 s2, s2, 63
	s_add_i32 s2, s2, s38
	v_lshl_or_b32 v70, s47, 7, v1
	v_and_or_b32 v80, v0, 15, s2
	v_mov_b32_e32 v71, v2
	v_readlane_b32 s54, v254, 50
	v_readlane_b32 s55, v254, 51
	v_ashrrev_i32_e32 v81, 31, v80
	v_lshlrev_b64 v[68:69], 2, v[70:71]
	v_lshlrev_b64 v[0:1], 12, v[80:81]
	v_lshl_add_u64 v[82:83], s[54:55], 0, v[68:69]
	v_lshl_add_u64 v[72:73], s[42:43], 0, v[68:69]
	v_lshl_add_u64 v[68:69], v[82:83], 0, v[0:1]
	v_or_b32_e32 v0, 16, v80
	v_ashrrev_i32_e32 v1, 31, v0
	v_lshlrev_b64 v[0:1], 12, v[0:1]
	v_lshl_add_u64 v[0:1], v[82:83], 0, v[0:1]
	v_or_b32_e32 v84, 32, v80
	v_ashrrev_i32_e32 v85, 31, v84
	v_lshlrev_b64 v[84:85], 12, v[84:85]
	v_lshl_add_u64 v[84:85], v[82:83], 0, v[84:85]
	v_or_b32_e32 v86, 48, v80
	v_ashrrev_i32_e32 v87, 31, v86
	v_lshlrev_b64 v[86:87], 12, v[86:87]
	v_lshl_add_u64 v[86:87], v[82:83], 0, v[86:87]
	v_or_b32_e32 v88, 16, v70
	v_mov_b32_e32 v89, v2
	v_lshl_add_u64 v[88:89], v[88:89], 2, s[42:43]
	v_or_b32_e32 v90, 32, v70
	v_mov_b32_e32 v91, v2
	v_lshl_add_u64 v[90:91], v[90:91], 2, s[42:43]
	v_or_b32_e32 v92, 48, v70
	v_mov_b32_e32 v93, v2
	v_lshl_add_u64 v[92:93], v[92:93], 2, s[42:43]
	s_mov_b64 s[38:39], 0
	s_and_b64 vcc, exec, s[40:41]
	s_mov_b32 s47, s45
	s_mov_b32 s48, s44
	s_movk_i32 s35, 0x2fff
	s_mov_b32 s34, s88
	v_readlane_b32 s19, v254, 62
	v_readlane_b32 s53, v254, 49
	v_readlane_b32 s58, v254, 54
	v_readlane_b32 s59, v254, 55
	global_load_dwordx4 v[72:75], v[72:73], off
	global_load_dwordx4 v[100:103], v[88:89], off
	global_load_dwordx4 v[104:107], v[90:91], off
	global_load_dwordx4 v[108:111], v[92:93], off
	global_load_dwordx4 v[112:115], v[68:69], off
	global_load_dwordx4 v[116:119], v[0:1], off
	global_load_dwordx4 v[120:123], v[84:85], off
	global_load_dwordx4 v[124:127], v[86:87], off
	global_load_dwordx4 v[128:131], v[68:69], off offset:64
	global_load_dwordx4 v[132:135], v[0:1], off offset:64
	global_load_dwordx4 v[136:139], v[84:85], off offset:64
	global_load_dwordx4 v[140:143], v[86:87], off offset:64
	global_load_dwordx4 v[144:147], v[68:69], off offset:128
	global_load_dwordx4 v[148:151], v[0:1], off offset:128
	global_load_dwordx4 v[152:155], v[84:85], off offset:128
	global_load_dwordx4 v[156:159], v[86:87], off offset:128
	global_load_dwordx4 v[160:163], v[68:69], off offset:192
	global_load_dwordx4 v[164:167], v[0:1], off offset:192
	global_load_dwordx4 v[76:79], v[84:85], off offset:192
	global_load_dwordx4 v[94:97], v[86:87], off offset:192
	s_waitcnt vmcnt(15)
	v_pk_fma_f32 v[66:67], v[66:67], v[74:75], v[114:115]
	v_pk_fma_f32 v[64:65], v[64:65], v[72:73], v[112:113]
	global_store_dwordx4 v[68:69], v[64:67], off
	s_waitcnt vmcnt(15)
	v_pk_fma_f32 v[62:63], v[62:63], v[74:75], v[118:119]
	v_pk_fma_f32 v[60:61], v[60:61], v[72:73], v[116:117]
	global_store_dwordx4 v[0:1], v[60:63], off
	s_waitcnt vmcnt(15)
	v_pk_fma_f32 v[58:59], v[58:59], v[74:75], v[122:123]
	v_pk_fma_f32 v[56:57], v[56:57], v[72:73], v[120:121]
	global_store_dwordx4 v[84:85], v[56:59], off
	s_waitcnt vmcnt(15)
	v_pk_fma_f32 v[54:55], v[54:55], v[74:75], v[126:127]
	v_pk_fma_f32 v[52:53], v[52:53], v[72:73], v[124:125]
	global_store_dwordx4 v[86:87], v[52:55], off
	s_waitcnt vmcnt(15)
	v_pk_fma_f32 v[50:51], v[50:51], v[102:103], v[130:131]
	v_pk_fma_f32 v[48:49], v[48:49], v[100:101], v[128:129]
	global_store_dwordx4 v[68:69], v[48:51], off offset:64
	s_waitcnt vmcnt(15)
	v_pk_fma_f32 v[46:47], v[46:47], v[102:103], v[134:135]
	v_pk_fma_f32 v[44:45], v[44:45], v[100:101], v[132:133]
	global_store_dwordx4 v[0:1], v[44:47], off offset:64
	s_waitcnt vmcnt(15)
	v_pk_fma_f32 v[42:43], v[42:43], v[102:103], v[138:139]
	v_pk_fma_f32 v[40:41], v[40:41], v[100:101], v[136:137]
	global_store_dwordx4 v[84:85], v[40:43], off offset:64
	s_waitcnt vmcnt(15)
	v_pk_fma_f32 v[38:39], v[38:39], v[102:103], v[142:143]
	v_pk_fma_f32 v[36:37], v[36:37], v[100:101], v[140:141]
	global_store_dwordx4 v[86:87], v[36:39], off offset:64
	s_waitcnt vmcnt(15)
	v_pk_fma_f32 v[34:35], v[34:35], v[106:107], v[146:147]
	v_pk_fma_f32 v[32:33], v[32:33], v[104:105], v[144:145]
	global_store_dwordx4 v[68:69], v[32:35], off offset:128
	s_waitcnt vmcnt(15)
	v_pk_fma_f32 v[30:31], v[30:31], v[106:107], v[150:151]
	v_pk_fma_f32 v[28:29], v[28:29], v[104:105], v[148:149]
	global_store_dwordx4 v[0:1], v[28:31], off offset:128
	s_waitcnt vmcnt(15)
	v_pk_fma_f32 v[26:27], v[26:27], v[106:107], v[154:155]
	v_pk_fma_f32 v[24:25], v[24:25], v[104:105], v[152:153]
	global_store_dwordx4 v[84:85], v[24:27], off offset:128
	s_waitcnt vmcnt(15)
	v_pk_fma_f32 v[22:23], v[22:23], v[106:107], v[158:159]
	v_pk_fma_f32 v[20:21], v[20:21], v[104:105], v[156:157]
	global_store_dwordx4 v[86:87], v[20:23], off offset:128
	s_waitcnt vmcnt(15)
	v_pk_fma_f32 v[18:19], v[18:19], v[110:111], v[162:163]
	v_pk_fma_f32 v[16:17], v[16:17], v[108:109], v[160:161]
	global_store_dwordx4 v[68:69], v[16:19], off offset:192
	s_waitcnt vmcnt(15)
	v_pk_fma_f32 v[14:15], v[14:15], v[110:111], v[166:167]
	v_pk_fma_f32 v[12:13], v[12:13], v[108:109], v[164:165]
	global_store_dwordx4 v[0:1], v[12:15], off offset:192
	s_waitcnt vmcnt(15)
	v_pk_fma_f32 v[10:11], v[10:11], v[110:111], v[78:79]
	v_pk_fma_f32 v[8:9], v[8:9], v[108:109], v[76:77]
	global_store_dwordx4 v[84:85], v[8:11], off offset:192
	s_waitcnt vmcnt(15)
	v_pk_fma_f32 v[6:7], v[6:7], v[110:111], v[96:97]
	v_pk_fma_f32 v[4:5], v[4:5], v[108:109], v[94:95]
	global_store_dwordx4 v[86:87], v[4:7], off offset:192
	s_cbranch_vccnz .LBB0_152
